# indexer loop: head-half sums combined with v_permlane32_swap instead of 4 ds_bpermute round trips per key tile
# speedup vs baseline: 1.0027x; 1.0027x over previous
; #define LAS __attribute__((address_space(3)))
; DI void indexer_unit(LAS unsigned char* lds, LAS unsigned long long* smask_w, const bf16_t* PROJ, const bf16_t* KIDXb, const int* posb, int mb0  , int t_0, int njp, int wave, int lane_in) {
;     ...
;     for (int jp = 0; jp < njp; ++jp) {
;         const bool pre = (jp + 1 < njp);
;         u32x4 preg = (u32x4){0u, 0u, 0u, 0u};
;         if (pre) preg = *(const u32x4*)(KIDXb + (size_t)(64 * (jp + 1) + srow) * 64 + sch * 8);
;         const LAS unsigned char* kb = kst + (jp & 1) * 8192;
;         float tot[2][2];
; #pragma unroll
;         for (int hh = 0; hh < 2; ++hh) {
;             const int rowl = 32 * hh + r; const LAS unsigned char* rb = kb + rowl * 128; const int sw = (rowl >> 1) & 7;
;             bf16x8 bk[4];
; #pragma unroll
;             for (int s2 = 0; s2 < 4; ++s2) bk[s2] = *(const LAS bf16x8*)(rb + (((2 * s2 + h) ^ sw) * 16));
; #pragma unroll
;             for (int ct = 0; ct < 2; ++ct) {
;                 f32x16 acc;
; #pragma unroll
;                 for (int i = 0; i < 16; ++i) acc[i] = 0.f;
; #pragma unroll
;                 for (int s2 = 0; s2 < 4; ++s2) acc = __builtin_amdgcn_mfma_f32_32x32x16_bf16(aq[ct][s2], bk[s2], acc, 0, 0, 0);
;                 float p = 0.f;
; #pragma unroll
;                 for (int i = 0; i < 16; ++i) p += wv[ct][i] * __builtin_amdgcn_fmed3f(acc[i], 0.f, __builtin_inff());
;                 p += __shfl_xor(p, 32);
;                 tot[ct][hh] = p;
;             }
;         }
;         const int key = 64 * jp + lane; const int pk = posb[key];
;         sc0[key] = (pk <= pos_t0) ? (h ? tot[0][1] : tot[0][0]) : -INFINITY;
;         sc1[key] = (pk <= pos_t1) ? (h ? tot[1][1] : tot[1][0]) : -INFINITY;
;         if (pre) *(LAS u32x4*)(kst + ((jp + 1) & 1) * 8192 + slo) = preg;
.LBB0_528:
	v_ashrrev_i32_e32 v245, 31, v96
	v_mov_b32_e32 v244, v96
	v_lshl_add_u64 v[244:245], v[244:245], 2, s[30:31]
	global_load_dword v243, v[244:245], off
	s_and_b32 s50, s45, 0x2000
	v_add_u32_e32 v4, s50, v133
	v_add_u32_e32 v5, v4, v135
	ds_read_b128 v[0:3], v5
	ds_read_b128 v[86:89], v5 offset:4096
	v_add_u32_e32 v5, v4, v136
	ds_read_b128 v[140:143], v5
	ds_read_b128 v[78:81], v5 offset:4096
	v_add_u32_e32 v5, v4, v137
	s_waitcnt lgkmcnt(3)
	v_mfma_f32_32x32x16_bf16 v[22:37], v[50:53], v[0:3], 0
	ds_read_b128 v[146:149], v5
	ds_read_b128 v[74:77], v5 offset:4096
	v_add_u32_e32 v4, v4, v138
	s_waitcnt lgkmcnt(3)
	v_mfma_f32_32x32x16_bf16 v[22:37], v[38:41], v[140:143], v[22:37]
	v_mfma_f32_32x32x16_bf16 v[6:21], v[62:65], v[0:3], 0
	ds_read_b128 v[0:3], v4
	ds_read_b128 v[82:85], v4 offset:4096
	s_waitcnt lgkmcnt(3)
	v_mfma_f32_32x32x16_bf16 v[22:37], v[42:45], v[146:149], v[22:37]
	v_mfma_f32_32x32x16_bf16 v[6:21], v[54:57], v[140:143], v[6:21]
	s_waitcnt lgkmcnt(1)
	v_mfma_f32_32x32x16_bf16 v[22:37], v[46:49], v[0:3], v[22:37]
	v_mfma_f32_32x32x16_bf16 v[6:21], v[58:61], v[146:149], v[6:21]
	s_nop 10
	v_max_f32_e32 v4, 0, v22
	v_max_f32_e32 v5, 0, v23
	v_max_f32_e32 v22, 0, v24
	v_max_f32_e32 v24, 0, v26
	v_max_f32_e32 v26, 0, v28
	v_max_f32_e32 v28, 0, v30
	v_max_f32_e32 v30, 0, v32
	v_fma_f32 v32, v101, v4, 0
	v_max_f32_e32 v23, 0, v25
	v_fmac_f32_e32 v32, v102, v5
	v_mfma_f32_32x32x16_bf16 v[6:21], v[66:69], v[0:3], v[6:21]
	v_fmac_f32_e32 v32, v103, v22
	v_max_f32_e32 v25, 0, v27
	v_fmac_f32_e32 v32, v104, v23
	v_fmac_f32_e32 v32, v105, v24
	v_max_f32_e32 v27, 0, v29
	v_fmac_f32_e32 v32, v106, v25
	v_fmac_f32_e32 v32, v107, v26
	v_max_f32_e32 v29, 0, v31
	v_fmac_f32_e32 v32, v108, v27
	v_fmac_f32_e32 v32, v109, v28
	v_max_f32_e32 v31, v33, v33
	v_fmac_f32_e32 v32, v110, v29
	v_max_f32_e32 v0, 0, v6
	v_fmac_f32_e32 v32, v111, v30
	v_max_f32_e32 v4, 0, v31
	v_fmac_f32_e32 v32, v112, v4
	v_max_f32_e32 v4, 0, v34
	v_fma_f32 v34, v117, v0, 0
	v_max_f32_e32 v0, 0, v7
	v_fmac_f32_e32 v34, v118, v0
	v_max_f32_e32 v0, 0, v8
	v_fmac_f32_e32 v34, v119, v0
	v_max_f32_e32 v0, 0, v9
	v_fmac_f32_e32 v34, v120, v0
	v_max_f32_e32 v0, 0, v10
	v_fmac_f32_e32 v34, v121, v0
	v_max_f32_e32 v0, 0, v11
	v_fmac_f32_e32 v32, v113, v4
	v_max_f32_e32 v4, 0, v35
	v_fmac_f32_e32 v34, v122, v0
	v_max_f32_e32 v0, 0, v12
	v_fmac_f32_e32 v32, v114, v4
	v_max_f32_e32 v4, 0, v36
	v_fmac_f32_e32 v34, v123, v0
	v_max_f32_e32 v0, 0, v13
	v_fmac_f32_e32 v32, v115, v4
	v_max_f32_e32 v4, 0, v37
	v_fmac_f32_e32 v34, v124, v0
	v_max_f32_e32 v0, 0, v14
	v_fmac_f32_e32 v32, v116, v4
	v_fmac_f32_e32 v34, v125, v0
	v_max_f32_e32 v22, 0, v15
	v_mfma_f32_32x32x16_bf16 v[0:15], v[50:53], v[86:89], 0
	v_max_f32_e32 v16, 0, v16
	v_fmac_f32_e32 v34, v126, v22
	v_fmac_f32_e32 v34, v127, v16
	v_max_f32_e32 v16, 0, v17
	v_mfma_f32_32x32x16_bf16 v[0:15], v[38:41], v[78:81], v[0:15]
	v_fmac_f32_e32 v34, v128, v16
	v_max_f32_e32 v16, 0, v18
	v_fmac_f32_e32 v34, v129, v16
	v_max_f32_e32 v16, 0, v19
	v_fmac_f32_e32 v34, v130, v16
	v_mfma_f32_32x32x16_bf16 v[0:15], v[42:45], v[74:77], v[0:15]
	v_max_f32_e32 v16, 0, v20
	v_fmac_f32_e32 v34, v131, v16
	v_max_f32_e32 v16, 0, v21
	v_fmac_f32_e32 v34, v132, v16
	v_mov_b32_e32 v33, v32
	s_waitcnt lgkmcnt(0)
	v_mfma_f32_32x32x16_bf16 v[0:15], v[46:49], v[82:85], v[0:15]
	v_mov_b32_e32 v35, v34
	v_mfma_f32_32x32x16_bf16 v[16:31], v[62:65], v[86:89], 0
	v_permlane32_swap_b32_e32 v33, v32
	s_nop 8
	v_permlane32_swap_b32_e32 v35, v34
	v_max_f32_e32 v0, 0, v0
	v_fma_f32 v36, v101, v0, 0
	v_max_f32_e32 v0, 0, v1
	v_fmac_f32_e32 v36, v102, v0
	v_max_f32_e32 v0, 0, v2
	v_fmac_f32_e32 v36, v103, v0
	v_max_f32_e32 v0, 0, v3
	v_fmac_f32_e32 v36, v104, v0
	v_max_f32_e32 v0, 0, v4
	v_fmac_f32_e32 v36, v105, v0
	v_max_f32_e32 v0, 0, v5
	v_fmac_f32_e32 v36, v106, v0
	v_max_f32_e32 v0, 0, v6
	v_fmac_f32_e32 v36, v107, v0
	v_max_f32_e32 v0, 0, v7
	v_fmac_f32_e32 v36, v108, v0
	v_max_f32_e32 v0, 0, v8
	v_fmac_f32_e32 v36, v109, v0
	v_max_f32_e32 v0, 0, v9
	v_fmac_f32_e32 v36, v110, v0
	v_max_f32_e32 v0, 0, v10
	v_fmac_f32_e32 v36, v111, v0
	v_max_f32_e32 v0, v11, v11
	v_max_f32_e32 v2, 0, v0
	v_mfma_f32_32x32x16_bf16 v[16:31], v[54:57], v[78:81], v[16:31]
	v_fmac_f32_e32 v36, v112, v2
	v_max_f32_e32 v1, 0, v12
	v_fmac_f32_e32 v36, v113, v1
	v_max_f32_e32 v1, 0, v13
	v_fmac_f32_e32 v36, v114, v1
	v_mfma_f32_32x32x16_bf16 v[16:31], v[58:61], v[74:77], v[16:31]
	v_max_f32_e32 v1, 0, v14
	v_fmac_f32_e32 v36, v115, v1
	v_max_f32_e32 v1, 0, v15
	v_fmac_f32_e32 v36, v116, v1
	v_mov_b32_e32 v1, v36
	v_mfma_f32_32x32x16_bf16 v[16:31], v[66:69], v[82:85], v[16:31]
	v_add_f32_e32 v4, v32, v33
	v_permlane32_swap_b32_e32 v1, v36
	v_add_f32_e32 v5, v34, v35
	v_add_f32_e32 v1, v36, v1
	v_cndmask_b32_e64 v1, v1, v4, s[0:1]
	s_nop 6
	v_max_f32_e32 v2, 0, v16
	v_max_f32_e32 v3, 0, v17
	v_fma_f32 v2, v117, v2, 0
	v_fmac_f32_e32 v2, v118, v3
	v_max_f32_e32 v3, 0, v18
	v_fmac_f32_e32 v2, v119, v3
	v_max_f32_e32 v3, 0, v19
	v_fmac_f32_e32 v2, v120, v3
	v_max_f32_e32 v3, 0, v20
	v_fmac_f32_e32 v2, v121, v3
	v_max_f32_e32 v3, 0, v21
	v_fmac_f32_e32 v2, v122, v3
	v_max_f32_e32 v3, 0, v22
	v_fmac_f32_e32 v2, v123, v3
	v_max_f32_e32 v3, 0, v23
	v_fmac_f32_e32 v2, v124, v3
	v_max_f32_e32 v3, 0, v24
	v_fmac_f32_e32 v2, v125, v3
	v_max_f32_e32 v3, 0, v25
	v_fmac_f32_e32 v2, v126, v3
	v_max_f32_e32 v3, 0, v26
	v_fmac_f32_e32 v2, v127, v3
	v_max_f32_e32 v3, 0, v27
	v_fmac_f32_e32 v2, v128, v3
	v_max_f32_e32 v3, 0, v28
	v_fmac_f32_e32 v2, v129, v3
	v_max_f32_e32 v3, 0, v29
	v_fmac_f32_e32 v2, v130, v3
	v_max_f32_e32 v3, 0, v30
	v_fmac_f32_e32 v2, v131, v3
	v_max_f32_e32 v3, 0, v31
	v_fmac_f32_e32 v2, v132, v3
	v_mov_b32_e32 v3, v2
	s_nop 1
	v_permlane32_swap_b32_e32 v3, v2
	v_add_f32_e32 v2, v2, v3
	v_cndmask_b32_e64 v2, v2, v5, s[0:1]
	s_waitcnt vmcnt(0)
	v_cmp_le_i32_e32 vcc, v243, v90
	s_nop 1
	v_cndmask_b32_e32 v1, v155, v1, vcc
	v_cmp_le_i32_e32 vcc, v243, v91
	s_nop 1
	v_cndmask_b32_e32 v0, v155, v2, vcc
	s_andn2_b64 vcc, exec, s[4:5]
	s_mov_b64 s[4:5], -1
	ds_write2st64_b32 v139, v1, v0 offset1:32
	s_cbranch_vccnz .LBB0_530
	s_add_i32 s50, s45, 0x2000
	s_mov_b64 s[4:5], 0
